# v22 + the 8 serialized census-check loads after the first phase barrier issued as one batch
# speedup vs baseline: 1.0154x; 1.0089x over previous
.LBB0_519:
	s_or_b64 exec, exec, s[0:1]
	v_readlane_b32 s0, v252, 0
	s_cmpk_eq_i32 s0, 0x100
	s_waitcnt lgkmcnt(0)
	s_barrier
	v_readlane_b32 s1, v252, 1
	s_cbranch_scc0 .LBB0_528
	s_waitcnt vmcnt(0)
	v_mov_b32_e32 v0, 0
	v_mov_b32_e32 v1, 0x3900000
	global_load_dword v2, v0, s[2:3] sc1
	global_load_dword v3, v1, s[54:55] offset:256 sc1
	global_load_dword v4, v1, s[54:55] offset:512 sc1
	global_load_dword v5, v1, s[54:55] offset:768 sc1
	global_load_dword v6, v1, s[54:55] offset:1024 sc1
	global_load_dword v7, v1, s[54:55] offset:1280 sc1
	global_load_dword v8, v1, s[54:55] offset:1536 sc1
	global_load_dword v9, v1, s[54:55] offset:1792 sc1
	s_waitcnt vmcnt(0)
	v_cmp_ne_u32_e32 vcc, 32, v2
	s_cbranch_vccnz .LBB0_529
	v_cmp_ne_u32_e32 vcc, 32, v3
	s_cbranch_vccnz .LBB0_529
	v_cmp_ne_u32_e32 vcc, 32, v4
	s_cbranch_vccnz .LBB0_529
	v_cmp_ne_u32_e32 vcc, 32, v5
	s_cbranch_vccnz .LBB0_529
	v_cmp_ne_u32_e32 vcc, 32, v6
	s_cbranch_vccnz .LBB0_529
	v_cmp_ne_u32_e32 vcc, 32, v7
	s_cbranch_vccnz .LBB0_529
	s_mov_b32 s0, s65
	v_cmp_ne_u32_e32 vcc, 32, v8
	s_cbranch_vccnz .LBB0_530
	v_readfirstlane_b32 s0, v9
	s_cmp_eq_u32 s0, 32
	s_cselect_b32 s0, s30, s65
	s_branch .LBB0_530
